# accumulator zeroing paired into v_mov_b64 (64 instead of 128 moves per GEMM unit)
# speedup vs baseline: 1.0065x; 1.0029x over previous
;     __device__ bool next(int i, pg8::Unit& u) const { if (i != 0 || !valid) return false; u.pm = pm; u.pn = pn; return true; }
; template <class Epi, class Sched, bool STAMP = false>
; __device__ __forceinline__ void gemm_phase(PG8_LAS unsigned char* lds, const Gemm g, const Sched& S, const Epi& E, unsigned long long* stamps) {
;     ...
;         const bool has_next = S.next(ui + 1, nxt);
;         const char* nA = has_next ? (const char*)g.A + (size_t)nxt.pm * tstep : cA; const char* nB = has_next ? (const char*)g.Bt + (size_t)nxt.pn * tstep : cB;
;     ...
; #pragma unroll
;         for (int a = 0; a < 2; ++a)
; #pragma unroll
;             for (int b = 0; b < 2; ++b)
; #pragma unroll
;                 for (int m = 0; m < 4; ++m)
; #pragma unroll
;                     for (int n = 0; n < 2; ++n) acc[a][b][m][n] = (f32x4){0.f, 0.f, 0.f, 0.f};
.LBB0_43:
	s_ashr_i32 s7, s6, 31
	v_cmp_lt_i64_e32 vcc, s[12:13], v[132:133]
	s_lshl_b64 s[12:13], s[6:7], 19
	s_add_u32 s12, s37, s12
	s_addc_u32 s13, s40, s13
	s_and_b64 s[14:15], vcc, exec
	s_cselect_b32 s7, s13, s25
	s_cselect_b32 s57, s12, s24
	s_ashr_i32 s5, s4, 31
	s_lshl_b64 s[14:15], s[4:5], 19
	s_add_u32 s20, s41, s14
	s_addc_u32 s21, s42, s15
	s_and_b64 s[14:15], vcc, exec
	s_cselect_b32 s5, s21, s27
	s_cselect_b32 s58, s20, s26
	s_add_u32 s24, s24, 0x40080
	s_addc_u32 s25, s25, 0
	s_add_u32 s59, s26, 0x100
	v_mov_b32_e32 v0, 0
	s_addc_u32 s60, s27, 0
	s_mov_b32 s61, -2
	v_mov_b32_e32 v1, v0
	v_mov_b64_e32 v[2:3], 0
	v_mov_b64_e32 v[4:5], 0
	v_mov_b64_e32 v[6:7], 0
	v_mov_b64_e32 v[16:17], 0
	v_mov_b64_e32 v[18:19], 0
	v_mov_b64_e32 v[20:21], 0
	v_mov_b64_e32 v[22:23], 0
	v_mov_b64_e32 v[32:33], 0
	v_mov_b64_e32 v[34:35], 0
	v_mov_b64_e32 v[36:37], 0
	v_mov_b64_e32 v[38:39], 0
	v_mov_b64_e32 v[48:49], 0
	v_mov_b64_e32 v[50:51], 0
	v_mov_b64_e32 v[52:53], 0
	v_mov_b64_e32 v[54:55], 0
	v_mov_b64_e32 v[8:9], 0
	v_mov_b64_e32 v[10:11], 0
	v_mov_b64_e32 v[12:13], 0
	v_mov_b64_e32 v[14:15], 0
	v_mov_b64_e32 v[24:25], 0
	v_mov_b64_e32 v[26:27], 0
	v_mov_b64_e32 v[28:29], 0
	v_mov_b64_e32 v[30:31], 0
	v_mov_b64_e32 v[40:41], 0
	v_mov_b64_e32 v[42:43], 0
	v_mov_b64_e32 v[44:45], 0
	v_mov_b64_e32 v[46:47], 0
	v_mov_b64_e32 v[56:57], 0
	v_mov_b64_e32 v[58:59], 0
	v_mov_b64_e32 v[60:61], 0
	v_mov_b64_e32 v[62:63], 0
	v_mov_b64_e32 v[64:65], 0
	v_mov_b64_e32 v[66:67], 0
	v_mov_b64_e32 v[68:69], 0
	v_mov_b64_e32 v[70:71], 0
	v_mov_b64_e32 v[80:81], 0
	v_mov_b64_e32 v[82:83], 0
	v_mov_b64_e32 v[84:85], 0
	v_mov_b64_e32 v[86:87], 0
	v_mov_b64_e32 v[96:97], 0
	v_mov_b64_e32 v[98:99], 0
	v_mov_b64_e32 v[100:101], 0
	v_mov_b64_e32 v[102:103], 0
	v_mov_b64_e32 v[112:113], 0
	v_mov_b64_e32 v[114:115], 0
	v_mov_b64_e32 v[116:117], 0
	v_mov_b64_e32 v[118:119], 0
	v_mov_b64_e32 v[72:73], 0
	v_mov_b64_e32 v[74:75], 0
	v_mov_b64_e32 v[76:77], 0
	v_mov_b64_e32 v[78:79], 0
	v_mov_b64_e32 v[88:89], 0
	v_mov_b64_e32 v[90:91], 0
	v_mov_b64_e32 v[92:93], 0
	v_mov_b64_e32 v[94:95], 0
	v_mov_b64_e32 v[104:105], 0
	v_mov_b64_e32 v[106:107], 0
	v_mov_b64_e32 v[108:109], 0
	v_mov_b64_e32 v[110:111], 0
	v_mov_b64_e32 v[120:121], 0
	v_mov_b64_e32 v[122:123], 0
	v_mov_b64_e32 v[124:125], 0
	v_mov_b64_e32 v[126:127], 0
	v_add_u32_e32 v244, 0x80, v128
	v_add_u32_e32 v245, 0x80, v148
	v_add_u32_e32 v246, 0x80, v152
	v_add_u32_e32 v247, 0x80, v150
	v_add_u32_e32 v248, 0x10000, v166
	v_add_u32_e32 v249, 0x14000, v166
	v_add_u32_e32 v250, 0x18000, v166
	v_add_u32_e32 v251, 0x1c000, v166

;     __device__ bool next(int i, pg8::Unit& u) const { if (i != 0 || !valid) return false; u.pm = pm; u.pn = pn; return true; }
; template <class Epi, class Sched, bool STAMP = false>
; __device__ __forceinline__ void gemm_phase(PG8_LAS unsigned char* lds, const Gemm g, const Sched& S, const Epi& E, unsigned long long* stamps) {
;     ...
;         const bool has_next = S.next(ui + 1, nxt);
;         const char* nA = has_next ? (const char*)g.A + (size_t)nxt.pm * tstep : cA; const char* nB = has_next ? (const char*)g.Bt + (size_t)nxt.pn * tstep : cB;
;     ...
; #pragma unroll
;         for (int a = 0; a < 2; ++a)
; #pragma unroll
;             for (int b = 0; b < 2; ++b)
; #pragma unroll
;                 for (int m = 0; m < 4; ++m)
; #pragma unroll
;                     for (int n = 0; n < 2; ++n) acc[a][b][m][n] = (f32x4){0.f, 0.f, 0.f, 0.f};
.LBB0_140:
	s_ashr_i32 s23, s22, 31
	s_lshl_b64 s[14:15], s[22:23], 19
	v_cmp_lt_i64_e32 vcc, s[24:25], v[136:137]
	s_add_u32 s24, s60, s14
	s_addc_u32 s25, s61, s15
	s_and_b64 s[14:15], vcc, exec
	s_cselect_b32 s23, s25, s45
	s_cselect_b32 s31, s24, s44
	s_ashr_i32 s21, s20, 31
	s_lshl_b64 s[14:15], s[20:21], 19
	s_add_u32 s26, s62, s14
	s_addc_u32 s27, s63, s15
	s_and_b64 s[14:15], vcc, exec
	s_cselect_b32 s21, s27, s49
	s_cselect_b32 vcc_lo, s26, s48
	s_add_u32 vcc_hi, s48, 0x100
	v_mov_b32_e32 v0, 0
	s_addc_u32 s38, s49, 0
	s_mov_b32 s39, -2
	s_waitcnt lgkmcnt(0)
	v_mov_b32_e32 v1, v0
	v_mov_b64_e32 v[2:3], 0
	v_mov_b64_e32 v[4:5], 0
	v_mov_b64_e32 v[6:7], 0
	v_mov_b64_e32 v[16:17], 0
	v_mov_b64_e32 v[18:19], 0
	v_mov_b64_e32 v[20:21], 0
	v_mov_b64_e32 v[22:23], 0
	v_mov_b64_e32 v[32:33], 0
	v_mov_b64_e32 v[34:35], 0
	v_mov_b64_e32 v[36:37], 0
	v_mov_b64_e32 v[38:39], 0
	v_mov_b64_e32 v[48:49], 0
	v_mov_b64_e32 v[50:51], 0
	v_mov_b64_e32 v[52:53], 0
	v_mov_b64_e32 v[54:55], 0
	v_mov_b64_e32 v[8:9], 0
	v_mov_b64_e32 v[10:11], 0
	v_mov_b64_e32 v[12:13], 0
	v_mov_b64_e32 v[14:15], 0
	v_mov_b64_e32 v[24:25], 0
	v_mov_b64_e32 v[26:27], 0
	v_mov_b64_e32 v[28:29], 0
	v_mov_b64_e32 v[30:31], 0
	v_mov_b64_e32 v[40:41], 0
	v_mov_b64_e32 v[42:43], 0
	v_mov_b64_e32 v[44:45], 0
	v_mov_b64_e32 v[46:47], 0
	v_mov_b64_e32 v[56:57], 0
	v_mov_b64_e32 v[58:59], 0
	v_mov_b64_e32 v[60:61], 0
	v_mov_b64_e32 v[62:63], 0
	v_mov_b64_e32 v[64:65], 0
	v_mov_b64_e32 v[66:67], 0
	v_mov_b64_e32 v[68:69], 0
	v_mov_b64_e32 v[70:71], 0
	v_mov_b64_e32 v[80:81], 0
	v_mov_b64_e32 v[82:83], 0
	v_mov_b64_e32 v[84:85], 0
	v_mov_b64_e32 v[86:87], 0
	v_mov_b64_e32 v[96:97], 0
	v_mov_b64_e32 v[98:99], 0
	v_mov_b64_e32 v[100:101], 0
	v_mov_b64_e32 v[102:103], 0
	v_mov_b64_e32 v[112:113], 0
	v_mov_b64_e32 v[114:115], 0
	v_mov_b64_e32 v[116:117], 0
	v_mov_b64_e32 v[118:119], 0
	v_mov_b64_e32 v[72:73], 0
	v_mov_b64_e32 v[74:75], 0
	v_mov_b64_e32 v[76:77], 0
	v_mov_b64_e32 v[78:79], 0
	v_mov_b64_e32 v[88:89], 0
	v_mov_b64_e32 v[90:91], 0
	v_mov_b64_e32 v[92:93], 0
	v_mov_b64_e32 v[94:95], 0
	v_mov_b64_e32 v[104:105], 0
	v_mov_b64_e32 v[106:107], 0
	v_mov_b64_e32 v[108:109], 0
	v_mov_b64_e32 v[110:111], 0
	v_mov_b64_e32 v[120:121], 0
	v_mov_b64_e32 v[122:123], 0
	v_mov_b64_e32 v[124:125], 0
	v_mov_b64_e32 v[126:127], 0
	v_add_u32_e32 v244, 0x80, v148
	v_add_u32_e32 v245, 0x80, v150
	v_add_u32_e32 v248, 0x10000, v166
	v_add_u32_e32 v249, 0x14000, v166
	v_add_u32_e32 v250, 0x18000, v166
	v_add_u32_e32 v251, 0x1c000, v166

; #define PG8_STAGE(bufoff, gbase, voff) do { _Pragma("unroll") for (int _i = 0; _i < 2; ++_i) \
;         __builtin_amdgcn_global_load_lds((const unsigned*)((const char*)(gbase) + (voff)[_i]), (PG8_LAS unsigned*)(lds + (bufoff) + ldsw + _i * 8192), 16, 0, 0); } while (0)
; #define PG8_WAIT_V(n) asm volatile("s_waitcnt vmcnt(" #n ")" ::: "memory")
; #define PG8_BAR __builtin_amdgcn_s_barrier()
; template <class Epi, class Sched, bool STAMP = false>
; __device__ __forceinline__ void gemm_phase(PG8_LAS unsigned char* lds, const Gemm g, const Sched& S, const Epi& E, unsigned long long* stamps) {
;     ...
;     f32x4 acc[2][2][4][2];
; #pragma unroll
;     for (int a = 0; a < 2; ++a)
; #pragma unroll
;         for (int b = 0; b < 2; ++b)
; #pragma unroll
;             for (int m = 0; m < 4; ++m)
; #pragma unroll
;                 for (int n = 0; n < 2; ++n) acc[a][b][m][n] = (f32x4){0.f, 0.f, 0.f, 0.f};
;     ...
;     PG8_STAGE(PG8_SB(0, 0), cB, voffB); PG8_STAGE(PG8_SA(0, 0), cA, voffA); PG8_STAGE(PG8_SB(0, 1), cB + hstep, voffB); PG8_STAGE(PG8_SA(0, 1), cA + hstep, voffA);
;     if (wr == 1) PG8_BAR;
;     PG8_WAIT_V(4); PG8_BAR;
;     PG8_STAGE(PG8_SB(1, 0), cB + kstep, voffB); PG8_STAGE(PG8_SA(1, 0), cA + kstep, voffA); PG8_STAGE(PG8_SB(1, 1), cB + hstep + kstep, voffB);
;     PG8_WAIT_V(6); PG8_BAR;
.LBB0_212:
	v_bfe_u32 v139, v0, 4, 2
	s_lshl_b32 s12, s12, 5
	v_and_b32_e32 v150, 15, v0
	v_lshlrev_b32_e32 v1, 4, v139
	v_lshlrev_b32_e32 v0, 2, v0
	s_and_b32 s56, s12, 0x60
	v_lshl_add_u64 v[2:3], s[0:1], 0, v[128:129]
	v_mov_b32_e32 v149, v129
	s_lshl_b32 s53, s13, 6
	v_lshl_or_b32 v1, v150, 6, v1
	s_lshl_b32 s13, s13, 13
	v_and_b32_e32 v0, 32, v0
	s_lshl_b32 s12, s56, 7
	v_lshl_add_u64 v[4:5], s[0:1], 0, v[148:149]
	v_bitop3_b32 v10, v1, s13, v0 bitop3:0xde
	v_bitop3_b32 v151, v1, s12, v0 bitop3:0xde
	s_add_i32 m0, s45, 0x18000
	v_lshl_add_u64 v[0:1], v[2:3], 0, s[18:19]
	v_lshl_add_u64 v[6:7], s[4:5], 0, v[128:129]
	s_waitcnt vmcnt(4)
	s_barrier
	global_load_lds_dwordx4 v[0:1], off
	v_lshl_add_u64 v[0:1], v[4:5], 0, s[18:19]
	s_add_i32 m0, s45, 0x1a000
	s_add_i32 s57, s45, 0x8000
	s_add_i32 s58, s45, 0xa000
	v_lshl_add_u64 v[8:9], s[4:5], 0, v[148:149]
	global_load_lds_dwordx4 v[0:1], off
	v_lshl_add_u64 v[0:1], v[6:7], 0, s[18:19]
	s_mov_b32 m0, s57
	s_add_u32 s12, s0, 0x40080
	global_load_lds_dwordx4 v[0:1], off
	v_lshl_add_u64 v[0:1], v[8:9], 0, s[18:19]
	s_mov_b32 m0, s58
	s_addc_u32 s13, s1, 0
	global_load_lds_dwordx4 v[0:1], off
	s_add_i32 m0, s45, 0x1c000
	v_lshl_add_u64 v[0:1], s[12:13], 0, v[128:129]
	global_load_lds_dwordx4 v[0:1], off
	v_lshl_add_u64 v[0:1], s[12:13], 0, v[148:149]
	s_add_i32 m0, s45, 0x1e000
	s_mov_b32 s14, 0
	global_load_lds_dwordx4 v[0:1], off
	s_waitcnt vmcnt(6)
	v_mov_b32_e32 v0, 0
	s_mov_b64 s[12:13], -1
	s_mov_b64 s[20:21], 0
	v_add_u32_e32 v152, 0, v10
	v_mov_b32_e32 v1, v0
	v_mov_b64_e32 v[2:3], 0
	v_mov_b64_e32 v[4:5], 0
	v_mov_b64_e32 v[6:7], 0
	v_mov_b64_e32 v[8:9], 0
	v_mov_b64_e32 v[10:11], 0
	v_mov_b64_e32 v[12:13], 0
	v_mov_b64_e32 v[14:15], 0
	v_mov_b64_e32 v[24:25], 0
	v_mov_b64_e32 v[26:27], 0
	v_mov_b64_e32 v[28:29], 0
	v_mov_b64_e32 v[30:31], 0
	v_mov_b64_e32 v[40:41], 0
	v_mov_b64_e32 v[42:43], 0
	v_mov_b64_e32 v[44:45], 0
	v_mov_b64_e32 v[46:47], 0
	v_mov_b64_e32 v[16:17], 0
	v_mov_b64_e32 v[18:19], 0
	v_mov_b64_e32 v[20:21], 0
	v_mov_b64_e32 v[22:23], 0
	v_mov_b64_e32 v[32:33], 0
	v_mov_b64_e32 v[34:35], 0
	v_mov_b64_e32 v[36:37], 0
	v_mov_b64_e32 v[38:39], 0
	v_mov_b64_e32 v[48:49], 0
	v_mov_b64_e32 v[50:51], 0
	v_mov_b64_e32 v[52:53], 0
	v_mov_b64_e32 v[54:55], 0
	v_mov_b64_e32 v[56:57], 0
	v_mov_b64_e32 v[58:59], 0
	v_mov_b64_e32 v[60:61], 0
	v_mov_b64_e32 v[62:63], 0
	v_mov_b64_e32 v[64:65], 0
	v_mov_b64_e32 v[66:67], 0
	v_mov_b64_e32 v[68:69], 0
	v_mov_b64_e32 v[70:71], 0
	v_mov_b64_e32 v[72:73], 0
	v_mov_b64_e32 v[74:75], 0
	v_mov_b64_e32 v[76:77], 0
	v_mov_b64_e32 v[78:79], 0
	v_mov_b64_e32 v[84:85], 0
	v_mov_b64_e32 v[86:87], 0
	v_mov_b64_e32 v[92:93], 0
	v_mov_b64_e32 v[94:95], 0
	v_mov_b64_e32 v[100:101], 0
	v_mov_b64_e32 v[102:103], 0
	v_mov_b64_e32 v[108:109], 0
	v_mov_b64_e32 v[110:111], 0
	v_mov_b64_e32 v[80:81], 0
	v_mov_b64_e32 v[82:83], 0
	v_mov_b64_e32 v[88:89], 0
	v_mov_b64_e32 v[90:91], 0
	v_mov_b64_e32 v[96:97], 0
	v_mov_b64_e32 v[98:99], 0
	v_mov_b64_e32 v[104:105], 0
	v_mov_b64_e32 v[106:107], 0
	v_mov_b64_e32 v[112:113], 0
	v_mov_b64_e32 v[114:115], 0
	v_mov_b64_e32 v[116:117], 0
	v_mov_b64_e32 v[118:119], 0
	v_mov_b64_e32 v[120:121], 0
	v_mov_b64_e32 v[122:123], 0
	v_mov_b64_e32 v[124:125], 0
	v_mov_b64_e32 v[126:127], 0
	s_barrier
	v_add_u32_e32 v244, 0x80, v128
	v_add_u32_e32 v245, 0x80, v148
	v_add_u32_e32 v248, 0x10000, v151
	v_add_u32_e32 v249, 0x14000, v151
	v_add_u32_e32 v250, 0x18000, v151
	v_add_u32_e32 v251, 0x1c000, v151

;     __device__ bool next(int i, pg8::Unit& u) const { if (i != 0 || !valid) return false; u.pm = pm; u.pn = pn; return true; }
; template <class Epi, class Sched, bool STAMP = false>
; __device__ __forceinline__ void gemm_phase(PG8_LAS unsigned char* lds, const Gemm g, const Sched& S, const Epi& E, unsigned long long* stamps) {
;     ...
;         const bool has_next = S.next(ui + 1, nxt);
;         const char* nA = has_next ? (const char*)g.A + (size_t)nxt.pm * tstep : cA; const char* nB = has_next ? (const char*)g.Bt + (size_t)nxt.pn * tstep : cB;
;     ...
; #pragma unroll
;         for (int a = 0; a < 2; ++a)
; #pragma unroll
;             for (int b = 0; b < 2; ++b)
; #pragma unroll
;                 for (int m = 0; m < 4; ++m)
; #pragma unroll
;                     for (int n = 0; n < 2; ++n) acc[a][b][m][n] = (f32x4){0.f, 0.f, 0.f, 0.f};
.LBB0_292:
	s_ashr_i32 s7, s6, 31
	v_cmp_lt_i64_e32 vcc, s[12:13], v[136:137]
	s_lshl_b64 s[12:13], s[6:7], 18
	s_add_u32 s12, s20, s12
	s_addc_u32 s13, s21, s13
	s_and_b64 s[14:15], vcc, exec
	s_cselect_b32 s7, s13, s25
	s_cselect_b32 s53, s12, s24
	s_ashr_i32 s5, s4, 31
	s_lshl_b64 s[14:15], s[4:5], 18
	s_add_u32 s22, s44, s14
	s_addc_u32 s23, s45, s15
	s_and_b64 s[14:15], vcc, exec
	s_cselect_b32 s5, s23, s27
	s_cselect_b32 s56, s22, s26
	s_add_u32 s24, s24, 0x20080
	s_addc_u32 s25, s25, 0
	s_add_u32 s57, s26, 0x100
	v_mov_b32_e32 v0, 0
	s_addc_u32 s58, s27, 0
	s_mov_b32 s59, -2
	v_mov_b32_e32 v1, v0
	v_mov_b64_e32 v[2:3], 0
	v_mov_b64_e32 v[4:5], 0
	v_mov_b64_e32 v[6:7], 0
	v_mov_b64_e32 v[8:9], 0
	v_mov_b64_e32 v[10:11], 0
	v_mov_b64_e32 v[12:13], 0
	v_mov_b64_e32 v[14:15], 0
	v_mov_b64_e32 v[24:25], 0
	v_mov_b64_e32 v[26:27], 0
	v_mov_b64_e32 v[28:29], 0
	v_mov_b64_e32 v[30:31], 0
	v_mov_b64_e32 v[40:41], 0
	v_mov_b64_e32 v[42:43], 0
	v_mov_b64_e32 v[44:45], 0
	v_mov_b64_e32 v[46:47], 0
	v_mov_b64_e32 v[16:17], 0
	v_mov_b64_e32 v[18:19], 0
	v_mov_b64_e32 v[20:21], 0
	v_mov_b64_e32 v[22:23], 0
	v_mov_b64_e32 v[32:33], 0
	v_mov_b64_e32 v[34:35], 0
	v_mov_b64_e32 v[36:37], 0
	v_mov_b64_e32 v[38:39], 0
	v_mov_b64_e32 v[48:49], 0
	v_mov_b64_e32 v[50:51], 0
	v_mov_b64_e32 v[52:53], 0
	v_mov_b64_e32 v[54:55], 0
	v_mov_b64_e32 v[56:57], 0
	v_mov_b64_e32 v[58:59], 0
	v_mov_b64_e32 v[60:61], 0
	v_mov_b64_e32 v[62:63], 0
	v_mov_b64_e32 v[64:65], 0
	v_mov_b64_e32 v[66:67], 0
	v_mov_b64_e32 v[68:69], 0
	v_mov_b64_e32 v[70:71], 0
	v_mov_b64_e32 v[72:73], 0
	v_mov_b64_e32 v[74:75], 0
	v_mov_b64_e32 v[76:77], 0
	v_mov_b64_e32 v[78:79], 0
	v_mov_b64_e32 v[88:89], 0
	v_mov_b64_e32 v[90:91], 0
	v_mov_b64_e32 v[92:93], 0
	v_mov_b64_e32 v[94:95], 0
	v_mov_b64_e32 v[104:105], 0
	v_mov_b64_e32 v[106:107], 0
	v_mov_b64_e32 v[108:109], 0
	v_mov_b64_e32 v[110:111], 0
	v_mov_b64_e32 v[80:81], 0
	v_mov_b64_e32 v[82:83], 0
	v_mov_b64_e32 v[84:85], 0
	v_mov_b64_e32 v[86:87], 0
	v_mov_b64_e32 v[96:97], 0
	v_mov_b64_e32 v[98:99], 0
	v_mov_b64_e32 v[100:101], 0
	v_mov_b64_e32 v[102:103], 0
	v_mov_b64_e32 v[112:113], 0
	v_mov_b64_e32 v[114:115], 0
	v_mov_b64_e32 v[116:117], 0
	v_mov_b64_e32 v[118:119], 0
	v_mov_b64_e32 v[120:121], 0
	v_mov_b64_e32 v[122:123], 0
	v_mov_b64_e32 v[124:125], 0
	v_mov_b64_e32 v[126:127], 0
	v_add_u32_e32 v244, 0x80, v128
	v_add_u32_e32 v245, 0x80, v152
	v_add_u32_e32 v246, 0x80, v148
	v_add_u32_e32 v247, 0x80, v150
	v_add_u32_e32 v248, 0x10000, v158
	v_add_u32_e32 v249, 0x14000, v158
	v_add_u32_e32 v250, 0x18000, v158
	v_add_u32_e32 v251, 0x1c000, v158

;     __device__ bool next(int i, pg8::Unit& u) const { if (i != 0 || !valid) return false; u.pm = pm; u.pn = pn; return true; }
; template <class Epi, class Sched, bool STAMP = false>
; __device__ __forceinline__ void gemm_phase(PG8_LAS unsigned char* lds, const Gemm g, const Sched& S, const Epi& E, unsigned long long* stamps) {
;     ...
;         const bool has_next = S.next(ui + 1, nxt);
;         const char* nA = has_next ? (const char*)g.A + (size_t)nxt.pm * tstep : cA; const char* nB = has_next ? (const char*)g.Bt + (size_t)nxt.pn * tstep : cB;
;     ...
; #pragma unroll
;         for (int a = 0; a < 2; ++a)
; #pragma unroll
;             for (int b = 0; b < 2; ++b)
; #pragma unroll
;                 for (int m = 0; m < 4; ++m)
; #pragma unroll
;                     for (int n = 0; n < 2; ++n) acc[a][b][m][n] = (f32x4){0.f, 0.f, 0.f, 0.f};
.LBB0_312:
	s_ashr_i32 s31, s30, 31
	s_lshl_b64 s[14:15], s[30:31], 19
	s_add_u32 s48, s42, s14
	v_cmp_lt_i64_e32 vcc, s[24:25], v[136:137]
	s_addc_u32 s49, s43, s15
	s_and_b64 s[14:15], vcc, exec
	s_cselect_b32 s31, s49, s5
	s_cselect_b32 s47, s48, s4
	s_ashr_i32 s7, s6, 31
	s_lshl_b64 s[14:15], s[6:7], 19
	s_add_u32 s24, s22, s14
	s_addc_u32 s25, s23, s15
	s_and_b64 s[14:15], vcc, exec
	s_cselect_b32 s7, s25, s13
	s_cselect_b32 s53, s24, s12
	s_add_u32 s4, s4, 0x40080
	s_addc_u32 s5, s5, 0
	s_add_u32 s62, s12, 0x100
	v_mov_b32_e32 v0, 0
	s_addc_u32 s63, s13, 0
	s_mov_b32 s65, -2
	v_mov_b32_e32 v1, v0
	v_mov_b64_e32 v[2:3], 0
	v_mov_b64_e32 v[4:5], 0
	v_mov_b64_e32 v[6:7], 0
	v_mov_b64_e32 v[16:17], 0
	v_mov_b64_e32 v[18:19], 0
	v_mov_b64_e32 v[20:21], 0
	v_mov_b64_e32 v[22:23], 0
	v_mov_b64_e32 v[32:33], 0
	v_mov_b64_e32 v[34:35], 0
	v_mov_b64_e32 v[36:37], 0
	v_mov_b64_e32 v[38:39], 0
	v_mov_b64_e32 v[48:49], 0
	v_mov_b64_e32 v[50:51], 0
	v_mov_b64_e32 v[52:53], 0
	v_mov_b64_e32 v[54:55], 0
	v_mov_b64_e32 v[8:9], 0
	v_mov_b64_e32 v[10:11], 0
	v_mov_b64_e32 v[12:13], 0
	v_mov_b64_e32 v[14:15], 0
	v_mov_b64_e32 v[24:25], 0
	v_mov_b64_e32 v[26:27], 0
	v_mov_b64_e32 v[28:29], 0
	v_mov_b64_e32 v[30:31], 0
	v_mov_b64_e32 v[40:41], 0
	v_mov_b64_e32 v[42:43], 0
	v_mov_b64_e32 v[44:45], 0
	v_mov_b64_e32 v[46:47], 0
	v_mov_b64_e32 v[56:57], 0
	v_mov_b64_e32 v[58:59], 0
	v_mov_b64_e32 v[60:61], 0
	v_mov_b64_e32 v[62:63], 0
	v_mov_b64_e32 v[64:65], 0
	v_mov_b64_e32 v[66:67], 0
	v_mov_b64_e32 v[68:69], 0
	v_mov_b64_e32 v[70:71], 0
	v_mov_b64_e32 v[80:81], 0
	v_mov_b64_e32 v[82:83], 0
	v_mov_b64_e32 v[84:85], 0
	v_mov_b64_e32 v[86:87], 0
	v_mov_b64_e32 v[96:97], 0
	v_mov_b64_e32 v[98:99], 0
	v_mov_b64_e32 v[100:101], 0
	v_mov_b64_e32 v[102:103], 0
	v_mov_b64_e32 v[112:113], 0
	v_mov_b64_e32 v[114:115], 0
	v_mov_b64_e32 v[116:117], 0
	v_mov_b64_e32 v[118:119], 0
	v_mov_b64_e32 v[72:73], 0
	v_mov_b64_e32 v[74:75], 0
	v_mov_b64_e32 v[76:77], 0
	v_mov_b64_e32 v[78:79], 0
	v_mov_b64_e32 v[88:89], 0
	v_mov_b64_e32 v[90:91], 0
	v_mov_b64_e32 v[92:93], 0
	v_mov_b64_e32 v[94:95], 0
	v_mov_b64_e32 v[104:105], 0
	v_mov_b64_e32 v[106:107], 0
	v_mov_b64_e32 v[108:109], 0
	v_mov_b64_e32 v[110:111], 0
	v_mov_b64_e32 v[120:121], 0
	v_mov_b64_e32 v[122:123], 0
	v_mov_b64_e32 v[124:125], 0
	v_mov_b64_e32 v[126:127], 0
	v_add_u32_e32 v244, 0x80, v128
	v_add_u32_e32 v245, 0x80, v152
	v_add_u32_e32 v246, 0x80, v148
	v_add_u32_e32 v247, 0x80, v150
	v_add_u32_e32 v248, 0x10000, v167
	v_add_u32_e32 v249, 0x14000, v167
	v_add_u32_e32 v250, 0x18000, v167
	v_add_u32_e32 v251, 0x1c000, v167

;     __device__ bool next(int i, pg8::Unit& u) const { if (i != 0 || !valid) return false; u.pm = pm; u.pn = pn; return true; }
; template <class Epi, class Sched, bool STAMP = false>
; __device__ __forceinline__ void gemm_phase(PG8_LAS unsigned char* lds, const Gemm g, const Sched& S, const Epi& E, unsigned long long* stamps) {
;     ...
;         const bool has_next = S.next(ui + 1, nxt);
;         const char* nA = has_next ? (const char*)g.A + (size_t)nxt.pm * tstep : cA; const char* nB = has_next ? (const char*)g.Bt + (size_t)nxt.pn * tstep : cB;
;     ...
; #pragma unroll
;         for (int a = 0; a < 2; ++a)
; #pragma unroll
;             for (int b = 0; b < 2; ++b)
; #pragma unroll
;                 for (int m = 0; m < 4; ++m)
; #pragma unroll
;                     for (int n = 0; n < 2; ++n) acc[a][b][m][n] = (f32x4){0.f, 0.f, 0.f, 0.f};
.LBB0_332:
	s_ashr_i32 s13, s12, 31
	s_lshl_b64 s[14:15], s[12:13], 18
	v_cmp_lt_i64_e32 vcc, s[24:25], v[136:137]
	s_add_u32 s24, s48, s14
	s_addc_u32 s25, s49, s15
	s_and_b64 s[14:15], vcc, exec
	s_cselect_b32 s13, s25, s37
	s_cselect_b32 s77, s24, s36
	s_ashr_i32 s5, s4, 31
	s_lshl_b64 s[14:15], s[4:5], 18
	s_add_u32 s26, s6, s14
	s_addc_u32 s27, s7, s15
	s_and_b64 s[14:15], vcc, exec
	s_cselect_b32 s5, s27, s57
	s_cselect_b32 s88, s26, s56
	s_add_u32 s36, s36, 0x20080
	s_addc_u32 s37, s37, 0
	s_add_u32 s89, s56, 0x100
	v_mov_b32_e32 v0, 0
	s_addc_u32 s96, s57, 0
	s_mov_b32 s97, -2
	v_mov_b32_e32 v1, v0
	v_mov_b64_e32 v[2:3], 0
	v_mov_b64_e32 v[4:5], 0
	v_mov_b64_e32 v[6:7], 0
	v_mov_b64_e32 v[8:9], 0
	v_mov_b64_e32 v[10:11], 0
	v_mov_b64_e32 v[12:13], 0
	v_mov_b64_e32 v[14:15], 0
	v_mov_b64_e32 v[24:25], 0
	v_mov_b64_e32 v[26:27], 0
	v_mov_b64_e32 v[28:29], 0
	v_mov_b64_e32 v[30:31], 0
	v_mov_b64_e32 v[40:41], 0
	v_mov_b64_e32 v[42:43], 0
	v_mov_b64_e32 v[44:45], 0
	v_mov_b64_e32 v[46:47], 0
	v_mov_b64_e32 v[16:17], 0
	v_mov_b64_e32 v[18:19], 0
	v_mov_b64_e32 v[20:21], 0
	v_mov_b64_e32 v[22:23], 0
	v_mov_b64_e32 v[32:33], 0
	v_mov_b64_e32 v[34:35], 0
	v_mov_b64_e32 v[36:37], 0
	v_mov_b64_e32 v[38:39], 0
	v_mov_b64_e32 v[48:49], 0
	v_mov_b64_e32 v[50:51], 0
	v_mov_b64_e32 v[52:53], 0
	v_mov_b64_e32 v[54:55], 0
	v_mov_b64_e32 v[56:57], 0
	v_mov_b64_e32 v[58:59], 0
	v_mov_b64_e32 v[60:61], 0
	v_mov_b64_e32 v[62:63], 0
	v_mov_b64_e32 v[64:65], 0
	v_mov_b64_e32 v[66:67], 0
	v_mov_b64_e32 v[68:69], 0
	v_mov_b64_e32 v[70:71], 0
	v_mov_b64_e32 v[72:73], 0
	v_mov_b64_e32 v[74:75], 0
	v_mov_b64_e32 v[76:77], 0
	v_mov_b64_e32 v[78:79], 0
	v_mov_b64_e32 v[88:89], 0
	v_mov_b64_e32 v[90:91], 0
	v_mov_b64_e32 v[92:93], 0
	v_mov_b64_e32 v[94:95], 0
	v_mov_b64_e32 v[104:105], 0
	v_mov_b64_e32 v[106:107], 0
	v_mov_b64_e32 v[108:109], 0
	v_mov_b64_e32 v[110:111], 0
	v_mov_b64_e32 v[80:81], 0
	v_mov_b64_e32 v[82:83], 0
	v_mov_b64_e32 v[84:85], 0
	v_mov_b64_e32 v[86:87], 0
	v_mov_b64_e32 v[96:97], 0
	v_mov_b64_e32 v[98:99], 0
	v_mov_b64_e32 v[100:101], 0
	v_mov_b64_e32 v[102:103], 0
	v_mov_b64_e32 v[112:113], 0
	v_mov_b64_e32 v[114:115], 0
	v_mov_b64_e32 v[116:117], 0
	v_mov_b64_e32 v[118:119], 0
	v_mov_b64_e32 v[120:121], 0
	v_mov_b64_e32 v[122:123], 0
	v_mov_b64_e32 v[124:125], 0
	v_mov_b64_e32 v[126:127], 0
	v_add_u32_e32 v244, 0x80, v128
	v_add_u32_e32 v245, 0x80, v152
	v_add_u32_e32 v246, 0x80, v148
	v_add_u32_e32 v247, 0x80, v150
	v_add_u32_e32 v248, 0x10000, v158
	v_add_u32_e32 v249, 0x14000, v158
	v_add_u32_e32 v250, 0x18000, v158
	v_add_u32_e32 v251, 0x1c000, v158

;     __device__ bool next(int i, pg8::Unit& u) const { if (i != 0 || !valid) return false; u.pm = pm; u.pn = pn; return true; }
; template <class Epi, class Sched, bool STAMP = false>
; __device__ __forceinline__ void gemm_phase(PG8_LAS unsigned char* lds, const Gemm g, const Sched& S, const Epi& E, unsigned long long* stamps) {
;     ...
;         const bool has_next = S.next(ui + 1, nxt);
;         const char* nA = has_next ? (const char*)g.A + (size_t)nxt.pm * tstep : cA; const char* nB = has_next ? (const char*)g.Bt + (size_t)nxt.pn * tstep : cB;
;     ...
; #pragma unroll
;         for (int a = 0; a < 2; ++a)
; #pragma unroll
;             for (int b = 0; b < 2; ++b)
; #pragma unroll
;                 for (int m = 0; m < 4; ++m)
; #pragma unroll
;                     for (int n = 0; n < 2; ++n) acc[a][b][m][n] = (f32x4){0.f, 0.f, 0.f, 0.f};
.LBB0_352:
	s_ashr_i32 s13, s12, 31
	v_cmp_lt_i64_e32 vcc, s[4:5], v[136:137]
	s_lshl_b64 s[4:5], s[12:13], 19
	s_add_u32 s4, s42, s4
	s_addc_u32 s5, s43, s5
	s_and_b64 s[14:15], vcc, exec
	s_cselect_b32 s13, s5, s57
	s_cselect_b32 s47, s4, s56
	s_ashr_i32 s27, s26, 31
	s_lshl_b64 s[14:15], s[26:27], 19
	s_add_u32 s36, s24, s14
	s_addc_u32 s37, s25, s15
	s_and_b64 s[14:15], vcc, exec
	s_cselect_b32 s27, s37, s59
	s_cselect_b32 s53, s36, s58
	s_add_u32 s56, s56, 0x40080
	s_addc_u32 s57, s57, 0
	s_add_u32 s76, s58, 0x100
	v_mov_b32_e32 v0, 0
	s_addc_u32 s77, s59, 0
	s_mov_b32 vcc_lo, -2
	v_mov_b32_e32 v1, v0
	v_mov_b64_e32 v[2:3], 0
	v_mov_b64_e32 v[4:5], 0
	v_mov_b64_e32 v[6:7], 0
	v_mov_b64_e32 v[16:17], 0
	v_mov_b64_e32 v[18:19], 0
	v_mov_b64_e32 v[20:21], 0
	v_mov_b64_e32 v[22:23], 0
	v_mov_b64_e32 v[32:33], 0
	v_mov_b64_e32 v[34:35], 0
	v_mov_b64_e32 v[36:37], 0
	v_mov_b64_e32 v[38:39], 0
	v_mov_b64_e32 v[48:49], 0
	v_mov_b64_e32 v[50:51], 0
	v_mov_b64_e32 v[52:53], 0
	v_mov_b64_e32 v[54:55], 0
	v_mov_b64_e32 v[8:9], 0
	v_mov_b64_e32 v[10:11], 0
	v_mov_b64_e32 v[12:13], 0
	v_mov_b64_e32 v[14:15], 0
	v_mov_b64_e32 v[24:25], 0
	v_mov_b64_e32 v[26:27], 0
	v_mov_b64_e32 v[28:29], 0
	v_mov_b64_e32 v[30:31], 0
	v_mov_b64_e32 v[40:41], 0
	v_mov_b64_e32 v[42:43], 0
	v_mov_b64_e32 v[44:45], 0
	v_mov_b64_e32 v[46:47], 0
	v_mov_b64_e32 v[56:57], 0
	v_mov_b64_e32 v[58:59], 0
	v_mov_b64_e32 v[60:61], 0
	v_mov_b64_e32 v[62:63], 0
	v_mov_b64_e32 v[64:65], 0
	v_mov_b64_e32 v[66:67], 0
	v_mov_b64_e32 v[68:69], 0
	v_mov_b64_e32 v[70:71], 0
	v_mov_b64_e32 v[80:81], 0
	v_mov_b64_e32 v[82:83], 0
	v_mov_b64_e32 v[84:85], 0
	v_mov_b64_e32 v[86:87], 0
	v_mov_b64_e32 v[96:97], 0
	v_mov_b64_e32 v[98:99], 0
	v_mov_b64_e32 v[100:101], 0
	v_mov_b64_e32 v[102:103], 0
	v_mov_b64_e32 v[112:113], 0
	v_mov_b64_e32 v[114:115], 0
	v_mov_b64_e32 v[116:117], 0
	v_mov_b64_e32 v[118:119], 0
	v_mov_b64_e32 v[72:73], 0
	v_mov_b64_e32 v[74:75], 0
	v_mov_b64_e32 v[76:77], 0
	v_mov_b64_e32 v[78:79], 0
	v_mov_b64_e32 v[88:89], 0
	v_mov_b64_e32 v[90:91], 0
	v_mov_b64_e32 v[92:93], 0
	v_mov_b64_e32 v[94:95], 0
	v_mov_b64_e32 v[104:105], 0
	v_mov_b64_e32 v[106:107], 0
	v_mov_b64_e32 v[108:109], 0
	v_mov_b64_e32 v[110:111], 0
	v_mov_b64_e32 v[120:121], 0
	v_mov_b64_e32 v[122:123], 0
	v_mov_b64_e32 v[124:125], 0
	v_mov_b64_e32 v[126:127], 0
	v_add_u32_e32 v244, 0x80, v128
	v_add_u32_e32 v245, 0x80, v152
	v_add_u32_e32 v246, 0x80, v148
	v_add_u32_e32 v247, 0x80, v150
	v_add_u32_e32 v248, 0x10000, v167
	v_add_u32_e32 v249, 0x14000, v167
	v_add_u32_e32 v250, 0x18000, v167
	v_add_u32_e32 v251, 0x1c000, v167

; #define PG8_STAGE(bufoff, gbase, voff) do { _Pragma("unroll") for (int _i = 0; _i < 2; ++_i) \
;         __builtin_amdgcn_global_load_lds((const unsigned*)((const char*)(gbase) + (voff)[_i]), (PG8_LAS unsigned*)(lds + (bufoff) + ldsw + _i * 8192), 16, 0, 0); } while (0)
; #define PG8_WAIT_V(n) asm volatile("s_waitcnt vmcnt(" #n ")" ::: "memory")
; #define PG8_BAR __builtin_amdgcn_s_barrier()
; template <class Epi, class Sched, bool STAMP = false>
; __device__ __forceinline__ void gemm_phase(PG8_LAS unsigned char* lds, const Gemm g, const Sched& S, const Epi& E, unsigned long long* stamps) {
;     ...
;     f32x4 acc[2][2][4][2];
; #pragma unroll
;     for (int a = 0; a < 2; ++a)
; #pragma unroll
;         for (int b = 0; b < 2; ++b)
; #pragma unroll
;             for (int m = 0; m < 4; ++m)
; #pragma unroll
;                 for (int n = 0; n < 2; ++n) acc[a][b][m][n] = (f32x4){0.f, 0.f, 0.f, 0.f};
;     ...
;     PG8_STAGE(PG8_SB(0, 0), cB, voffB); PG8_STAGE(PG8_SA(0, 0), cA, voffA); PG8_STAGE(PG8_SB(0, 1), cB + hstep, voffB); PG8_STAGE(PG8_SA(0, 1), cA + hstep, voffA);
;     if (wr == 1) PG8_BAR;
;     PG8_WAIT_V(4); PG8_BAR;
;     PG8_STAGE(PG8_SB(1, 0), cB + kstep, voffB); PG8_STAGE(PG8_SA(1, 0), cA + kstep, voffA); PG8_STAGE(PG8_SB(1, 1), cB + hstep + kstep, voffB);
;     PG8_WAIT_V(6); PG8_BAR;
.LBB0_373:
	v_bfe_u32 v139, v0, 4, 2
	s_lshl_b32 s14, s14, 5
	v_and_b32_e32 v150, 15, v0
	v_lshlrev_b32_e32 v1, 4, v139
	v_lshlrev_b32_e32 v0, 2, v0
	s_and_b32 s53, s14, 0x60
	v_lshl_add_u64 v[2:3], s[4:5], 0, v[128:129]
	v_mov_b32_e32 v149, v129
	s_lshl_b32 s49, s15, 6
	v_lshl_or_b32 v1, v150, 6, v1
	s_lshl_b32 s15, s15, 13
	v_and_b32_e32 v0, 32, v0
	s_lshl_b32 s14, s53, 7
	v_lshl_add_u64 v[4:5], s[4:5], 0, v[148:149]
	v_bitop3_b32 v14, v1, s15, v0 bitop3:0xde
	v_bitop3_b32 v151, v1, s14, v0 bitop3:0xde
	s_add_i32 m0, s42, 0x18000
	v_lshl_add_u64 v[0:1], v[2:3], 0, s[18:19]
	v_lshl_add_u64 v[6:7], s[6:7], 0, v[128:129]
	s_waitcnt vmcnt(4)
	s_barrier
	global_load_lds_dwordx4 v[0:1], off
	v_lshl_add_u64 v[0:1], v[4:5], 0, s[18:19]
	s_add_i32 m0, s42, 0x1a000
	s_add_i32 s56, s42, 0x8000
	v_lshl_add_u64 v[8:9], s[6:7], 0, v[148:149]
	global_load_lds_dwordx4 v[0:1], off
	v_lshl_add_u64 v[0:1], v[6:7], 0, s[18:19]
	s_mov_b32 m0, s56
	s_add_i32 s57, s42, 0xa000
	v_lshl_add_u64 v[10:11], s[20:21], 0, v[128:129]
	global_load_lds_dwordx4 v[0:1], off
	v_lshl_add_u64 v[0:1], v[8:9], 0, s[18:19]
	s_mov_b32 m0, s57
	v_lshl_add_u64 v[12:13], s[20:21], 0, v[148:149]
	global_load_lds_dwordx4 v[0:1], off
	s_add_i32 m0, s42, 0x1c000
	v_lshl_add_u64 v[0:1], v[10:11], 0, s[18:19]
	global_load_lds_dwordx4 v[0:1], off
	v_lshl_add_u64 v[0:1], v[12:13], 0, s[18:19]
	s_add_i32 m0, s42, 0x1e000
	s_mov_b32 s14, 0
	global_load_lds_dwordx4 v[0:1], off
	s_waitcnt vmcnt(6)
	v_mov_b32_e32 v0, 0
	s_mov_b64 s[20:21], -1
	s_mov_b64 s[22:23], 0
	v_add_u32_e32 v152, 0, v14
	v_mov_b32_e32 v1, v0
	v_mov_b64_e32 v[2:3], 0
	v_mov_b64_e32 v[4:5], 0
	v_mov_b64_e32 v[6:7], 0
	v_mov_b64_e32 v[8:9], 0
	v_mov_b64_e32 v[10:11], 0
	v_mov_b64_e32 v[12:13], 0
	v_mov_b64_e32 v[14:15], 0
	v_mov_b64_e32 v[24:25], 0
	v_mov_b64_e32 v[26:27], 0
	v_mov_b64_e32 v[28:29], 0
	v_mov_b64_e32 v[30:31], 0
	v_mov_b64_e32 v[40:41], 0
	v_mov_b64_e32 v[42:43], 0
	v_mov_b64_e32 v[44:45], 0
	v_mov_b64_e32 v[46:47], 0
	v_mov_b64_e32 v[16:17], 0
	v_mov_b64_e32 v[18:19], 0
	v_mov_b64_e32 v[20:21], 0
	v_mov_b64_e32 v[22:23], 0
	v_mov_b64_e32 v[32:33], 0
	v_mov_b64_e32 v[34:35], 0
	v_mov_b64_e32 v[36:37], 0
	v_mov_b64_e32 v[38:39], 0
	v_mov_b64_e32 v[48:49], 0
	v_mov_b64_e32 v[50:51], 0
	v_mov_b64_e32 v[52:53], 0
	v_mov_b64_e32 v[54:55], 0
	v_mov_b64_e32 v[56:57], 0
	v_mov_b64_e32 v[58:59], 0
	v_mov_b64_e32 v[60:61], 0
	v_mov_b64_e32 v[62:63], 0
	v_mov_b64_e32 v[64:65], 0
	v_mov_b64_e32 v[66:67], 0
	v_mov_b64_e32 v[68:69], 0
	v_mov_b64_e32 v[70:71], 0
	v_mov_b64_e32 v[72:73], 0
	v_mov_b64_e32 v[74:75], 0
	v_mov_b64_e32 v[76:77], 0
	v_mov_b64_e32 v[78:79], 0
	v_mov_b64_e32 v[84:85], 0
	v_mov_b64_e32 v[86:87], 0
	v_mov_b64_e32 v[92:93], 0
	v_mov_b64_e32 v[94:95], 0
	v_mov_b64_e32 v[100:101], 0
	v_mov_b64_e32 v[102:103], 0
	v_mov_b64_e32 v[108:109], 0
	v_mov_b64_e32 v[110:111], 0
	v_mov_b64_e32 v[80:81], 0
	v_mov_b64_e32 v[82:83], 0
	v_mov_b64_e32 v[88:89], 0
	v_mov_b64_e32 v[90:91], 0
	v_mov_b64_e32 v[96:97], 0
	v_mov_b64_e32 v[98:99], 0
	v_mov_b64_e32 v[104:105], 0
	v_mov_b64_e32 v[106:107], 0
	v_mov_b64_e32 v[112:113], 0
	v_mov_b64_e32 v[114:115], 0
	v_mov_b64_e32 v[116:117], 0
	v_mov_b64_e32 v[118:119], 0
	v_mov_b64_e32 v[120:121], 0
	v_mov_b64_e32 v[122:123], 0
	v_mov_b64_e32 v[124:125], 0
	v_mov_b64_e32 v[126:127], 0
	s_barrier
	v_add_u32_e32 v244, 0x80, v128
	v_add_u32_e32 v245, 0x80, v148
	v_add_u32_e32 v248, 0x10000, v151
	v_add_u32_e32 v249, 0x14000, v151
	v_add_u32_e32 v250, 0x18000, v151
	v_add_u32_e32 v251, 0x1c000, v151

;     __device__ bool next(int i, pg8::Unit& u) const { if (i != 0 || !valid) return false; u.pm = pm; u.pn = pn; return true; }
; template <class Epi, class Sched, bool STAMP = false>
; __device__ __forceinline__ void gemm_phase(PG8_LAS unsigned char* lds, const Gemm g, const Sched& S, const Epi& E, unsigned long long* stamps) {
;     ...
;         const bool has_next = S.next(ui + 1, nxt);
;         const char* nA = has_next ? (const char*)g.A + (size_t)nxt.pm * tstep : cA; const char* nB = has_next ? (const char*)g.Bt + (size_t)nxt.pn * tstep : cB;
;     ...
; #pragma unroll
;         for (int a = 0; a < 2; ++a)
; #pragma unroll
;             for (int b = 0; b < 2; ++b)
; #pragma unroll
;                 for (int m = 0; m < 4; ++m)
; #pragma unroll
;                     for (int n = 0; n < 2; ++n) acc[a][b][m][n] = (f32x4){0.f, 0.f, 0.f, 0.f};
.LBB0_494:
	s_ashr_i32 s7, s6, 31
	v_cmp_lt_i64_e32 vcc, s[12:13], v[142:143]
	s_lshl_b64 s[12:13], s[6:7], 19
	s_add_u32 s12, s37, s12
	s_addc_u32 s13, s40, s13
	s_and_b64 s[14:15], vcc, exec
	s_cselect_b32 s7, s13, s25
	s_cselect_b32 s57, s12, s24
	s_ashr_i32 s5, s4, 31
	s_lshl_b64 s[14:15], s[4:5], 19
	s_add_u32 s20, s41, s14
	s_addc_u32 s21, s42, s15
	s_and_b64 s[14:15], vcc, exec
	s_cselect_b32 s5, s21, s27
	s_cselect_b32 s58, s20, s26
	s_add_u32 s24, s24, 0x40080
	s_addc_u32 s25, s25, 0
	s_add_u32 s59, s26, 0x100
	v_mov_b32_e32 v0, 0
	s_addc_u32 s60, s27, 0
	s_mov_b32 s61, -2
	v_mov_b32_e32 v1, v0
	v_mov_b64_e32 v[2:3], 0
	v_mov_b64_e32 v[4:5], 0
	v_mov_b64_e32 v[6:7], 0
	v_mov_b64_e32 v[16:17], 0
	v_mov_b64_e32 v[18:19], 0
	v_mov_b64_e32 v[20:21], 0
	v_mov_b64_e32 v[22:23], 0
	v_mov_b64_e32 v[32:33], 0
	v_mov_b64_e32 v[34:35], 0
	v_mov_b64_e32 v[36:37], 0
	v_mov_b64_e32 v[38:39], 0
	v_mov_b64_e32 v[48:49], 0
	v_mov_b64_e32 v[50:51], 0
	v_mov_b64_e32 v[52:53], 0
	v_mov_b64_e32 v[54:55], 0
	v_mov_b64_e32 v[8:9], 0
	v_mov_b64_e32 v[10:11], 0
	v_mov_b64_e32 v[12:13], 0
	v_mov_b64_e32 v[14:15], 0
	v_mov_b64_e32 v[24:25], 0
	v_mov_b64_e32 v[26:27], 0
	v_mov_b64_e32 v[28:29], 0
	v_mov_b64_e32 v[30:31], 0
	v_mov_b64_e32 v[40:41], 0
	v_mov_b64_e32 v[42:43], 0
	v_mov_b64_e32 v[44:45], 0
	v_mov_b64_e32 v[46:47], 0
	v_mov_b64_e32 v[56:57], 0
	v_mov_b64_e32 v[58:59], 0
	v_mov_b64_e32 v[60:61], 0
	v_mov_b64_e32 v[62:63], 0
	v_mov_b64_e32 v[64:65], 0
	v_mov_b64_e32 v[66:67], 0
	v_mov_b64_e32 v[68:69], 0
	v_mov_b64_e32 v[70:71], 0
	v_mov_b64_e32 v[80:81], 0
	v_mov_b64_e32 v[82:83], 0
	v_mov_b64_e32 v[84:85], 0
	v_mov_b64_e32 v[86:87], 0
	v_mov_b64_e32 v[96:97], 0
	v_mov_b64_e32 v[98:99], 0
	v_mov_b64_e32 v[100:101], 0
	v_mov_b64_e32 v[102:103], 0
	v_mov_b64_e32 v[112:113], 0
	v_mov_b64_e32 v[114:115], 0
	v_mov_b64_e32 v[116:117], 0
	v_mov_b64_e32 v[118:119], 0
	v_mov_b64_e32 v[72:73], 0
	v_mov_b64_e32 v[74:75], 0
	v_mov_b64_e32 v[76:77], 0
	v_mov_b32_e32 v78, v0
	s_waitcnt vmcnt(0)
	v_mov_b32_e32 v79, v0
	v_mov_b32_e32 v88, v0
	v_mov_b32_e32 v89, v0
	v_mov_b32_e32 v90, v0
	v_mov_b32_e32 v91, v0
	v_mov_b32_e32 v92, v0
	v_mov_b32_e32 v93, v0
	v_mov_b32_e32 v94, v0
	v_mov_b32_e32 v95, v0
	v_mov_b32_e32 v104, v0
	v_mov_b32_e32 v105, v0
	v_mov_b32_e32 v106, v0
	v_mov_b32_e32 v107, v0
	v_mov_b32_e32 v108, v0
	v_mov_b32_e32 v109, v0
	v_mov_b32_e32 v110, v0
	v_mov_b32_e32 v111, v0
	v_mov_b32_e32 v120, v0
	v_mov_b32_e32 v121, v0
	v_mov_b32_e32 v122, v0
	v_mov_b32_e32 v123, v0
	v_mov_b32_e32 v124, v0
	v_mov_b32_e32 v125, v0
	v_mov_b32_e32 v126, v0
	v_mov_b32_e32 v127, v0
	v_add_u32_e32 v244, 0x80, v128
	v_add_u32_e32 v245, 0x80, v148
	v_add_u32_e32 v246, 0x80, v152
	v_add_u32_e32 v247, 0x80, v150
	v_add_u32_e32 v248, 0x10000, v166
	v_add_u32_e32 v249, 0x14000, v166
	v_add_u32_e32 v250, 0x18000, v166
	v_add_u32_e32 v251, 0x1c000, v166

;     __device__ bool next(int i, pg8::Unit& u) const { if (i != 0 || !valid) return false; u.pm = pm; u.pn = pn; return true; }
; template <class Epi, class Sched, bool STAMP = false>
; __device__ __forceinline__ void gemm_phase(PG8_LAS unsigned char* lds, const Gemm g, const Sched& S, const Epi& E, unsigned long long* stamps) {
;     ...
;         const bool has_next = S.next(ui + 1, nxt);
;         const char* nA = has_next ? (const char*)g.A + (size_t)nxt.pm * tstep : cA; const char* nB = has_next ? (const char*)g.Bt + (size_t)nxt.pn * tstep : cB;
;     ...
; #pragma unroll
;         for (int a = 0; a < 2; ++a)
; #pragma unroll
;             for (int b = 0; b < 2; ++b)
; #pragma unroll
;                 for (int m = 0; m < 4; ++m)
; #pragma unroll
;                     for (int n = 0; n < 2; ++n) acc[a][b][m][n] = (f32x4){0.f, 0.f, 0.f, 0.f};
.LBB0_1182:
	s_ashr_i32 s7, s6, 31
	v_cmp_lt_i64_e32 vcc, s[12:13], v[136:137]
	s_lshl_b64 s[12:13], s[6:7], 21
	s_add_u32 s12, s45, s12
	s_addc_u32 s13, s46, s13
	s_and_b64 s[14:15], vcc, exec
	s_cselect_b32 s7, s13, s27
	s_cselect_b32 s23, s12, s26
	s_ashr_i32 s5, s4, 31
	s_lshl_b64 s[14:15], s[4:5], 21
	s_add_u32 s20, s47, s14
	s_addc_u32 s21, s48, s15
	s_and_b64 s[14:15], vcc, exec
	s_cselect_b32 s5, s21, s31
	s_cselect_b32 s62, s20, s30
	s_add_u32 s63, s30, 0x100
	v_mov_b32_e32 v0, 0
	s_addc_u32 s64, s31, 0
	s_mov_b32 s65, -2
	s_waitcnt lgkmcnt(0)
	v_mov_b32_e32 v1, v0
	v_mov_b64_e32 v[2:3], 0
	v_mov_b64_e32 v[4:5], 0
	v_mov_b64_e32 v[6:7], 0
	v_mov_b64_e32 v[16:17], 0
	v_mov_b64_e32 v[18:19], 0
	v_mov_b64_e32 v[20:21], 0
	v_mov_b64_e32 v[22:23], 0
	v_mov_b64_e32 v[32:33], 0
	v_mov_b64_e32 v[34:35], 0
	v_mov_b64_e32 v[36:37], 0
	v_mov_b64_e32 v[38:39], 0
	v_mov_b64_e32 v[48:49], 0
	v_mov_b64_e32 v[50:51], 0
	v_mov_b64_e32 v[52:53], 0
	v_mov_b64_e32 v[54:55], 0
	v_mov_b64_e32 v[8:9], 0
	v_mov_b64_e32 v[10:11], 0
	v_mov_b64_e32 v[12:13], 0
	v_mov_b64_e32 v[14:15], 0
	v_mov_b64_e32 v[24:25], 0
	v_mov_b64_e32 v[26:27], 0
	v_mov_b64_e32 v[28:29], 0
	v_mov_b64_e32 v[30:31], 0
	v_mov_b64_e32 v[40:41], 0
	v_mov_b64_e32 v[42:43], 0
	v_mov_b64_e32 v[44:45], 0
	v_mov_b64_e32 v[46:47], 0
	v_mov_b64_e32 v[56:57], 0
	v_mov_b64_e32 v[58:59], 0
	v_mov_b64_e32 v[60:61], 0
	v_mov_b64_e32 v[62:63], 0
	v_mov_b64_e32 v[64:65], 0
	v_mov_b64_e32 v[66:67], 0
	v_mov_b64_e32 v[68:69], 0
	v_mov_b64_e32 v[70:71], 0
	v_mov_b64_e32 v[80:81], 0
	v_mov_b64_e32 v[82:83], 0
	v_mov_b64_e32 v[84:85], 0
	v_mov_b64_e32 v[86:87], 0
	v_mov_b64_e32 v[96:97], 0
	s_waitcnt vmcnt(0)
	v_mov_b32_e32 v98, v0
	v_mov_b32_e32 v99, v0
	v_mov_b32_e32 v100, v0
	v_mov_b32_e32 v101, v0
	v_mov_b32_e32 v102, v0
	v_mov_b32_e32 v103, v0
	v_mov_b32_e32 v112, v0
	v_mov_b32_e32 v113, v0
	v_mov_b32_e32 v114, v0
	v_mov_b32_e32 v115, v0
	v_mov_b32_e32 v116, v0
	v_mov_b32_e32 v117, v0
	v_mov_b32_e32 v118, v0
	v_mov_b32_e32 v119, v0
	v_mov_b32_e32 v72, v0
	v_mov_b32_e32 v73, v0
	v_mov_b32_e32 v74, v0
	v_mov_b32_e32 v75, v0
	v_mov_b32_e32 v76, v0
	v_mov_b32_e32 v77, v0
	v_mov_b32_e32 v78, v0
	v_mov_b32_e32 v79, v0
	v_mov_b32_e32 v88, v0
	v_mov_b32_e32 v89, v0
	v_mov_b32_e32 v90, v0
	v_mov_b32_e32 v91, v0
	v_mov_b32_e32 v92, v0
	v_mov_b32_e32 v93, v0
	v_mov_b32_e32 v94, v0
	v_mov_b32_e32 v95, v0
	v_mov_b32_e32 v104, v0
	v_mov_b32_e32 v105, v0
	v_mov_b32_e32 v106, v0
	v_mov_b32_e32 v107, v0
	v_mov_b32_e32 v108, v0
	v_mov_b32_e32 v109, v0
	v_mov_b32_e32 v110, v0
	v_mov_b32_e32 v111, v0
	v_mov_b32_e32 v120, v0
	v_mov_b32_e32 v121, v0
	v_mov_b32_e32 v122, v0
	v_mov_b32_e32 v123, v0
	v_mov_b32_e32 v124, v0
	v_mov_b32_e32 v125, v0
	v_mov_b32_e32 v126, v0
	v_mov_b32_e32 v127, v0
	v_add_u32_e32 v244, 0x80, v128
	v_add_u32_e32 v245, 0x80, v148
	v_add_u32_e32 v248, 0x10000, v158
	v_add_u32_e32 v249, 0x14000, v158
	v_add_u32_e32 v250, 0x18000, v158
	v_add_u32_e32 v251, 0x1c000, v158

; #define PG8_STAGE(bufoff, gbase, voff) do { _Pragma("unroll") for (int _i = 0; _i < 2; ++_i) \
;         __builtin_amdgcn_global_load_lds((const unsigned*)((const char*)(gbase) + (voff)[_i]), (PG8_LAS unsigned*)(lds + (bufoff) + ldsw + _i * 8192), 16, 0, 0); } while (0)
; #define PG8_WAIT_V(n) asm volatile("s_waitcnt vmcnt(" #n ")" ::: "memory")
; #define PG8_BAR __builtin_amdgcn_s_barrier()
; template <class Epi, class Sched, bool STAMP = false>
; __device__ __forceinline__ void gemm_phase(PG8_LAS unsigned char* lds, const Gemm g, const Sched& S, const Epi& E, unsigned long long* stamps) {
;     ...
;     f32x4 acc[2][2][4][2];
; #pragma unroll
;     for (int a = 0; a < 2; ++a)
; #pragma unroll
;         for (int b = 0; b < 2; ++b)
; #pragma unroll
;             for (int m = 0; m < 4; ++m)
; #pragma unroll
;                 for (int n = 0; n < 2; ++n) acc[a][b][m][n] = (f32x4){0.f, 0.f, 0.f, 0.f};
;     ...
;     PG8_STAGE(PG8_SB(0, 0), cB, voffB); PG8_STAGE(PG8_SA(0, 0), cA, voffA); PG8_STAGE(PG8_SB(0, 1), cB + hstep, voffB); PG8_STAGE(PG8_SA(0, 1), cA + hstep, voffA);
;     if (wr == 1) PG8_BAR;
;     PG8_WAIT_V(4); PG8_BAR;
;     PG8_STAGE(PG8_SB(1, 0), cB + kstep, voffB); PG8_STAGE(PG8_SA(1, 0), cA + kstep, voffA); PG8_STAGE(PG8_SB(1, 1), cB + hstep + kstep, voffB);
;     PG8_WAIT_V(6); PG8_BAR;
.LBB0_1206:
	v_bfe_u32 v139, v12, 4, 2
	s_lshl_b32 s6, s6, 5
	v_and_b32_e32 v154, 15, v12
	v_lshlrev_b32_e32 v17, 4, v139
	v_lshlrev_b32_e32 v12, 2, v12
	s_and_b32 s36, s6, 0x60
	s_add_i32 m0, s27, 0x18000
	v_lshl_add_u64 v[6:7], v[6:7], 0, s[18:19]
	s_lshl_b32 s35, s7, 6
	v_lshl_or_b32 v17, v154, 6, v17
	s_lshl_b32 s7, s7, 13
	v_and_b32_e32 v12, 32, v12
	s_lshl_b32 s6, s36, 7
	s_waitcnt vmcnt(4)
	s_barrier
	global_load_lds_dwordx4 v[6:7], off
	v_lshl_add_u64 v[4:5], v[4:5], 0, s[18:19]
	s_add_i32 m0, s27, 0x1a000
	s_add_i32 s37, s27, 0x8000
	s_add_i32 s38, s27, 0xa000
	v_bitop3_b32 v155, v17, s6, v12 bitop3:0xde
	global_load_lds_dwordx4 v[4:5], off
	v_lshl_add_u64 v[2:3], v[2:3], 0, s[18:19]
	s_mov_b32 m0, s37
	s_add_u32 s6, s0, 0x100080
	v_bitop3_b32 v18, v17, s7, v12 bitop3:0xde
	global_load_lds_dwordx4 v[2:3], off
	v_lshl_add_u64 v[0:1], v[0:1], 0, s[18:19]
	s_mov_b32 m0, s38
	s_addc_u32 s7, s1, 0
	global_load_lds_dwordx4 v[0:1], off
	s_add_i32 m0, s27, 0x1c000
	v_lshl_add_u64 v[0:1], s[6:7], 0, v[128:129]
	global_load_lds_dwordx4 v[0:1], off
	v_lshl_add_u64 v[0:1], s[6:7], 0, v[148:149]
	s_add_i32 m0, s27, 0x1e000
	s_lshl_b32 s4, s4, 16
	global_load_lds_dwordx4 v[0:1], off
	s_and_b32 s4, s4, 0x600000
	s_or_b32 s4, s4, s5
	v_lshlrev_b32_e32 v0, 15, v14
	v_and_b32_e32 v0, 0x7fff0000, v0
	s_add_u32 s4, s10, s4
	v_lshl_add_u32 v0, v13, 12, v0
	s_addc_u32 s5, s42, 0
	v_or_b32_e32 v0, v0, v15
	s_add_u32 s4, s4, 0xd600080
	v_add_lshl_u32 v0, v0, v16, 1
	v_mov_b32_e32 v1, v129
	s_addc_u32 s5, s5, 0
	v_lshl_add_u64 v[150:151], s[4:5], 0, v[0:1]
	v_lshlrev_b32_e32 v0, 15, v8
	v_and_b32_e32 v0, 0x7fff0000, v0
	v_lshl_add_u32 v0, v9, 12, v0
	v_or_b32_e32 v0, v0, v10
	s_waitcnt vmcnt(6)
	v_add_lshl_u32 v0, v0, v11, 1
	v_lshl_add_u64 v[152:153], s[4:5], 0, v[0:1]
	v_mov_b32_e32 v0, 0
	s_mov_b32 s39, -2
	s_mov_b64 s[4:5], 0
	v_add_u32_e32 v156, 0, v18
	v_mov_b32_e32 v1, v0
	v_mov_b64_e32 v[2:3], 0
	v_mov_b64_e32 v[4:5], 0
	v_mov_b64_e32 v[6:7], 0
	v_mov_b64_e32 v[8:9], 0
	v_mov_b64_e32 v[10:11], 0
	v_mov_b64_e32 v[12:13], 0
	v_mov_b64_e32 v[14:15], 0
	v_mov_b64_e32 v[24:25], 0
	v_mov_b64_e32 v[26:27], 0
	v_mov_b64_e32 v[28:29], 0
	v_mov_b64_e32 v[30:31], 0
	v_mov_b64_e32 v[40:41], 0
	v_mov_b64_e32 v[42:43], 0
	v_mov_b64_e32 v[44:45], 0
	v_mov_b64_e32 v[46:47], 0
	v_mov_b64_e32 v[16:17], 0
	v_mov_b64_e32 v[18:19], 0
	v_mov_b64_e32 v[20:21], 0
	v_mov_b64_e32 v[22:23], 0
	v_mov_b64_e32 v[32:33], 0
	v_mov_b64_e32 v[34:35], 0
	v_mov_b64_e32 v[36:37], 0
	v_mov_b64_e32 v[38:39], 0
	v_mov_b64_e32 v[48:49], 0
	v_mov_b64_e32 v[50:51], 0
	v_mov_b64_e32 v[52:53], 0
	v_mov_b64_e32 v[54:55], 0
	v_mov_b64_e32 v[56:57], 0
	v_mov_b64_e32 v[58:59], 0
	v_mov_b64_e32 v[60:61], 0
	v_mov_b64_e32 v[62:63], 0
	v_mov_b64_e32 v[64:65], 0
	v_mov_b64_e32 v[66:67], 0
	v_mov_b64_e32 v[68:69], 0
	v_mov_b64_e32 v[70:71], 0
	v_mov_b64_e32 v[72:73], 0
	v_mov_b64_e32 v[74:75], 0
	v_mov_b64_e32 v[76:77], 0
	v_mov_b32_e32 v78, v0
	s_waitcnt vmcnt(0)
	v_mov_b32_e32 v79, v0
	v_mov_b32_e32 v84, v0
	v_mov_b32_e32 v85, v0
	v_mov_b32_e32 v86, v0
	v_mov_b32_e32 v87, v0
	v_mov_b32_e32 v92, v0
	v_mov_b32_e32 v93, v0
	v_mov_b32_e32 v94, v0
	v_mov_b32_e32 v95, v0
	v_mov_b32_e32 v100, v0
	v_mov_b32_e32 v101, v0
	v_mov_b32_e32 v102, v0
	v_mov_b32_e32 v103, v0
	v_mov_b32_e32 v108, v0
	v_mov_b32_e32 v109, v0
	v_mov_b32_e32 v110, v0
	v_mov_b32_e32 v111, v0
	v_mov_b32_e32 v80, v0
	v_mov_b32_e32 v81, v0
	v_mov_b32_e32 v82, v0
	v_mov_b32_e32 v83, v0
	v_mov_b32_e32 v88, v0
	v_mov_b32_e32 v89, v0
	v_mov_b32_e32 v90, v0
	v_mov_b32_e32 v91, v0
	v_mov_b32_e32 v96, v0
	v_mov_b32_e32 v97, v0
	v_mov_b32_e32 v98, v0
	v_mov_b32_e32 v99, v0
	v_mov_b32_e32 v104, v0
	v_mov_b32_e32 v105, v0
	v_mov_b32_e32 v106, v0
	v_mov_b32_e32 v107, v0
	v_mov_b32_e32 v112, v0
	v_mov_b32_e32 v113, v0
	v_mov_b32_e32 v114, v0
	v_mov_b32_e32 v115, v0
	v_mov_b32_e32 v116, v0
	v_mov_b32_e32 v117, v0
	v_mov_b32_e32 v118, v0
	v_mov_b32_e32 v119, v0
	v_mov_b32_e32 v120, v0
	v_mov_b32_e32 v121, v0
	v_mov_b32_e32 v122, v0
	v_mov_b32_e32 v123, v0
	v_mov_b32_e32 v124, v0
	v_mov_b32_e32 v125, v0
	v_mov_b32_e32 v126, v0
	v_mov_b32_e32 v127, v0
	s_barrier
	v_add_u32_e32 v244, 0x80, v128
	v_add_u32_e32 v245, 0x80, v148
	v_add_u32_e32 v248, 0x10000, v155
	v_add_u32_e32 v249, 0x14000, v155
	v_add_u32_e32 v250, 0x18000, v155
	v_add_u32_e32 v251, 0x1c000, v155

;     __device__ bool next(int i, pg8::Unit& u) const { if (i != 0 || !valid) return false; u.pm = pm; u.pn = pn; return true; }
; template <class Epi, class Sched, bool STAMP = false>
; __device__ __forceinline__ void gemm_phase(PG8_LAS unsigned char* lds, const Gemm g, const Sched& S, const Epi& E, unsigned long long* stamps) {
;     ...
;         const bool has_next = S.next(ui + 1, nxt);
;         const char* nA = has_next ? (const char*)g.A + (size_t)nxt.pm * tstep : cA; const char* nB = has_next ? (const char*)g.Bt + (size_t)nxt.pn * tstep : cB;
;     ...
; #pragma unroll
;         for (int a = 0; a < 2; ++a)
; #pragma unroll
;             for (int b = 0; b < 2; ++b)
; #pragma unroll
;                 for (int m = 0; m < 4; ++m)
; #pragma unroll
;                     for (int n = 0; n < 2; ++n) acc[a][b][m][n] = (f32x4){0.f, 0.f, 0.f, 0.f};
.LBB0_1339:
	s_ashr_i32 s7, s6, 31
	v_cmp_lt_i64_e32 vcc, s[12:13], v[146:147]
	s_lshl_b64 s[12:13], s[6:7], 19
	s_add_u32 s12, s37, s12
	s_addc_u32 s13, s40, s13
	s_and_b64 s[14:15], vcc, exec
	s_cselect_b32 s7, s13, s25
	s_cselect_b32 s57, s12, s24
	s_ashr_i32 s5, s4, 31
	s_lshl_b64 s[14:15], s[4:5], 19
	s_add_u32 s20, s36, s14
	s_addc_u32 s21, s10, s15
	s_and_b64 s[14:15], vcc, exec
	s_cselect_b32 s5, s21, s27
	s_cselect_b32 s58, s20, s26
	s_add_u32 s24, s24, 0x40080
	s_addc_u32 s25, s25, 0
	s_add_u32 s59, s26, 0x100
	v_mov_b32_e32 v0, 0
	s_addc_u32 s60, s27, 0
	s_mov_b32 s61, -2
	v_mov_b32_e32 v1, v0
	v_mov_b64_e32 v[2:3], 0
	v_mov_b64_e32 v[4:5], 0
	v_mov_b64_e32 v[6:7], 0
	v_mov_b64_e32 v[16:17], 0
	v_mov_b64_e32 v[18:19], 0
	v_mov_b64_e32 v[20:21], 0
	v_mov_b64_e32 v[22:23], 0
	v_mov_b64_e32 v[32:33], 0
	v_mov_b64_e32 v[34:35], 0
	v_mov_b64_e32 v[36:37], 0
	v_mov_b64_e32 v[38:39], 0
	v_mov_b64_e32 v[48:49], 0
	v_mov_b64_e32 v[50:51], 0
	v_mov_b64_e32 v[52:53], 0
	v_mov_b64_e32 v[54:55], 0
	v_mov_b64_e32 v[8:9], 0
	v_mov_b64_e32 v[10:11], 0
	v_mov_b64_e32 v[12:13], 0
	v_mov_b64_e32 v[14:15], 0
	v_mov_b64_e32 v[24:25], 0
	v_mov_b64_e32 v[26:27], 0
	v_mov_b64_e32 v[28:29], 0
	v_mov_b64_e32 v[30:31], 0
	v_mov_b64_e32 v[40:41], 0
	v_mov_b64_e32 v[42:43], 0
	v_mov_b64_e32 v[44:45], 0
	v_mov_b64_e32 v[46:47], 0
	v_mov_b64_e32 v[56:57], 0
	v_mov_b64_e32 v[58:59], 0
	v_mov_b64_e32 v[60:61], 0
	v_mov_b64_e32 v[62:63], 0
	v_mov_b64_e32 v[64:65], 0
	v_mov_b64_e32 v[66:67], 0
	v_mov_b64_e32 v[68:69], 0
	v_mov_b64_e32 v[70:71], 0
	v_mov_b64_e32 v[80:81], 0
	v_mov_b64_e32 v[82:83], 0
	v_mov_b64_e32 v[84:85], 0
	v_mov_b64_e32 v[86:87], 0
	v_mov_b64_e32 v[96:97], 0
	s_waitcnt vmcnt(0)
	v_mov_b32_e32 v98, v0
	v_mov_b32_e32 v99, v0
	v_mov_b32_e32 v100, v0
	v_mov_b32_e32 v101, v0
	v_mov_b32_e32 v102, v0
	v_mov_b32_e32 v103, v0
	v_mov_b32_e32 v112, v0
	v_mov_b32_e32 v113, v0
	v_mov_b32_e32 v114, v0
	v_mov_b32_e32 v115, v0
	v_mov_b32_e32 v116, v0
	v_mov_b32_e32 v117, v0
	v_mov_b32_e32 v118, v0
	v_mov_b32_e32 v119, v0
	v_mov_b32_e32 v72, v0
	v_mov_b32_e32 v73, v0
	v_mov_b32_e32 v74, v0
	v_mov_b32_e32 v75, v0
	v_mov_b32_e32 v76, v0
	v_mov_b32_e32 v77, v0
	v_mov_b32_e32 v78, v0
	v_mov_b32_e32 v79, v0
	v_mov_b32_e32 v88, v0
	v_mov_b32_e32 v89, v0
	v_mov_b32_e32 v90, v0
	v_mov_b32_e32 v91, v0
	v_mov_b32_e32 v92, v0
	v_mov_b32_e32 v93, v0
	v_mov_b32_e32 v94, v0
	v_mov_b32_e32 v95, v0
	v_mov_b32_e32 v104, v0
	v_mov_b32_e32 v105, v0
	v_mov_b32_e32 v106, v0
	v_mov_b32_e32 v107, v0
	v_mov_b32_e32 v108, v0
	v_mov_b32_e32 v109, v0
	v_mov_b32_e32 v110, v0
	v_mov_b32_e32 v111, v0
	v_mov_b32_e32 v120, v0
	v_mov_b32_e32 v121, v0
	v_mov_b32_e32 v122, v0
	v_mov_b32_e32 v123, v0
	v_mov_b32_e32 v124, v0
	v_mov_b32_e32 v125, v0
	v_mov_b32_e32 v126, v0
	v_mov_b32_e32 v127, v0
	v_add_u32_e32 v244, 0x80, v128
	v_add_u32_e32 v245, 0x80, v148
	v_add_u32_e32 v246, 0x80, v152
	v_add_u32_e32 v247, 0x80, v150
	v_add_u32_e32 v248, 0x10000, v166
	v_add_u32_e32 v249, 0x14000, v166
	v_add_u32_e32 v250, 0x18000, v166
	v_add_u32_e32 v251, 0x1c000, v166

; #define PG8_STAGE(bufoff, gbase, voff) do { _Pragma("unroll") for (int _i = 0; _i < 2; ++_i) \
;         __builtin_amdgcn_global_load_lds((const unsigned*)((const char*)(gbase) + (voff)[_i]), (PG8_LAS unsigned*)(lds + (bufoff) + ldsw + _i * 8192), 16, 0, 0); } while (0)
; #define PG8_WAIT_V(n) asm volatile("s_waitcnt vmcnt(" #n ")" ::: "memory")
; #define PG8_BAR __builtin_amdgcn_s_barrier()
; template <class Epi, class Sched, bool STAMP = false>
; __device__ __forceinline__ void gemm_phase(PG8_LAS unsigned char* lds, const Gemm g, const Sched& S, const Epi& E, unsigned long long* stamps) {
;     ...
;     f32x4 acc[2][2][4][2];
; #pragma unroll
;     for (int a = 0; a < 2; ++a)
; #pragma unroll
;         for (int b = 0; b < 2; ++b)
; #pragma unroll
;             for (int m = 0; m < 4; ++m)
; #pragma unroll
;                 for (int n = 0; n < 2; ++n) acc[a][b][m][n] = (f32x4){0.f, 0.f, 0.f, 0.f};
;     ...
;     PG8_STAGE(PG8_SB(0, 0), cB, voffB); PG8_STAGE(PG8_SA(0, 0), cA, voffA); PG8_STAGE(PG8_SB(0, 1), cB + hstep, voffB); PG8_STAGE(PG8_SA(0, 1), cA + hstep, voffA);
;     if (wr == 1) PG8_BAR;
;     PG8_WAIT_V(4); PG8_BAR;
;     PG8_STAGE(PG8_SB(1, 0), cB + kstep, voffB); PG8_STAGE(PG8_SA(1, 0), cA + kstep, voffA); PG8_STAGE(PG8_SB(1, 1), cB + hstep + kstep, voffB);
;     PG8_WAIT_V(6); PG8_BAR;
.LBB0_1348:
	v_bfe_u32 v139, v0, 4, 2
	s_lshl_b32 s14, s14, 5
	v_and_b32_e32 v150, 15, v0
	v_lshlrev_b32_e32 v1, 4, v139
	v_lshlrev_b32_e32 v0, 2, v0
	s_and_b32 s56, s14, 0x60
	v_lshl_add_u64 v[2:3], s[6:7], 0, v[128:129]
	v_mov_b32_e32 v149, v129
	s_lshl_b32 s53, s15, 6
	v_lshl_or_b32 v1, v150, 6, v1
	s_lshl_b32 s15, s15, 13
	v_and_b32_e32 v0, 32, v0
	s_lshl_b32 s14, s56, 7
	v_lshl_add_u64 v[4:5], s[6:7], 0, v[148:149]
	v_bitop3_b32 v10, v1, s15, v0 bitop3:0xde
	v_bitop3_b32 v151, v1, s14, v0 bitop3:0xde
	s_add_i32 m0, s10, 0x18000
	v_lshl_add_u64 v[0:1], v[2:3], 0, s[18:19]
	v_lshl_add_u64 v[6:7], s[12:13], 0, v[128:129]
	s_waitcnt vmcnt(4)
	s_barrier
	global_load_lds_dwordx4 v[0:1], off
	v_lshl_add_u64 v[0:1], v[4:5], 0, s[18:19]
	s_add_i32 m0, s10, 0x1a000
	s_add_i32 s57, s10, 0x8000
	s_add_i32 s58, s10, 0xa000
	v_lshl_add_u64 v[8:9], s[12:13], 0, v[148:149]
	global_load_lds_dwordx4 v[0:1], off
	v_lshl_add_u64 v[0:1], v[6:7], 0, s[18:19]
	s_mov_b32 m0, s57
	s_add_u32 s14, s6, 0x40080
	global_load_lds_dwordx4 v[0:1], off
	v_lshl_add_u64 v[0:1], v[8:9], 0, s[18:19]
	s_mov_b32 m0, s58
	s_addc_u32 s15, s7, 0
	global_load_lds_dwordx4 v[0:1], off
	s_add_i32 m0, s10, 0x1c000
	v_lshl_add_u64 v[0:1], s[14:15], 0, v[128:129]
	global_load_lds_dwordx4 v[0:1], off
	v_lshl_add_u64 v[0:1], s[14:15], 0, v[148:149]
	s_add_i32 m0, s10, 0x1e000
	s_mov_b32 s14, 0
	global_load_lds_dwordx4 v[0:1], off
	s_waitcnt vmcnt(6)
	v_mov_b32_e32 v0, 0
	s_mov_b64 s[22:23], -1
	s_mov_b64 s[24:25], 0
	v_add_u32_e32 v152, 0, v10
	v_mov_b32_e32 v1, v0
	v_mov_b64_e32 v[2:3], 0
	v_mov_b64_e32 v[4:5], 0
	v_mov_b64_e32 v[6:7], 0
	v_mov_b64_e32 v[8:9], 0
	v_mov_b64_e32 v[10:11], 0
	v_mov_b64_e32 v[12:13], 0
	v_mov_b64_e32 v[14:15], 0
	v_mov_b64_e32 v[24:25], 0
	v_mov_b64_e32 v[26:27], 0
	v_mov_b64_e32 v[28:29], 0
	v_mov_b64_e32 v[30:31], 0
	v_mov_b64_e32 v[40:41], 0
	v_mov_b64_e32 v[42:43], 0
	v_mov_b64_e32 v[44:45], 0
	v_mov_b64_e32 v[46:47], 0
	v_mov_b64_e32 v[16:17], 0
	v_mov_b64_e32 v[18:19], 0
	v_mov_b64_e32 v[20:21], 0
	v_mov_b64_e32 v[22:23], 0
	v_mov_b64_e32 v[32:33], 0
	v_mov_b64_e32 v[34:35], 0
	v_mov_b64_e32 v[36:37], 0
	v_mov_b64_e32 v[38:39], 0
	v_mov_b64_e32 v[48:49], 0
	v_mov_b64_e32 v[50:51], 0
	v_mov_b64_e32 v[52:53], 0
	v_mov_b64_e32 v[54:55], 0
	v_mov_b64_e32 v[56:57], 0
	v_mov_b64_e32 v[58:59], 0
	v_mov_b64_e32 v[60:61], 0
	v_mov_b64_e32 v[62:63], 0
	v_mov_b64_e32 v[64:65], 0
	v_mov_b64_e32 v[66:67], 0
	v_mov_b64_e32 v[68:69], 0
	v_mov_b64_e32 v[70:71], 0
	v_mov_b64_e32 v[72:73], 0
	v_mov_b64_e32 v[74:75], 0
	v_mov_b64_e32 v[76:77], 0
	v_mov_b32_e32 v78, v0
	s_waitcnt vmcnt(0)
	v_mov_b32_e32 v79, v0
	v_mov_b32_e32 v84, v0
	v_mov_b32_e32 v85, v0
	v_mov_b32_e32 v86, v0
	v_mov_b32_e32 v87, v0
	v_mov_b32_e32 v92, v0
	v_mov_b32_e32 v93, v0
	v_mov_b32_e32 v94, v0
	v_mov_b32_e32 v95, v0
	v_mov_b32_e32 v100, v0
	v_mov_b32_e32 v101, v0
	v_mov_b32_e32 v102, v0
	v_mov_b32_e32 v103, v0
	v_mov_b32_e32 v108, v0
	v_mov_b32_e32 v109, v0
	v_mov_b32_e32 v110, v0
	v_mov_b32_e32 v111, v0
	v_mov_b32_e32 v80, v0
	v_mov_b32_e32 v81, v0
	v_mov_b32_e32 v82, v0
	v_mov_b32_e32 v83, v0
	v_mov_b32_e32 v88, v0
	v_mov_b32_e32 v89, v0
	v_mov_b32_e32 v90, v0
	v_mov_b32_e32 v91, v0
	v_mov_b32_e32 v96, v0
	v_mov_b32_e32 v97, v0
	v_mov_b32_e32 v98, v0
	v_mov_b32_e32 v99, v0
	v_mov_b32_e32 v104, v0
	v_mov_b32_e32 v105, v0
	v_mov_b32_e32 v106, v0
	v_mov_b32_e32 v107, v0
	v_mov_b32_e32 v112, v0
	v_mov_b32_e32 v113, v0
	v_mov_b32_e32 v114, v0
	v_mov_b32_e32 v115, v0
	v_mov_b32_e32 v116, v0
	v_mov_b32_e32 v117, v0
	v_mov_b32_e32 v118, v0
	v_mov_b32_e32 v119, v0
	v_mov_b32_e32 v120, v0
	v_mov_b32_e32 v121, v0
	v_mov_b32_e32 v122, v0
	v_mov_b32_e32 v123, v0
	v_mov_b32_e32 v124, v0
	v_mov_b32_e32 v125, v0
	v_mov_b32_e32 v126, v0
	v_mov_b32_e32 v127, v0
	s_barrier
	v_add_u32_e32 v244, 0x80, v128
	v_add_u32_e32 v245, 0x80, v148
	v_add_u32_e32 v248, 0x10000, v151
	v_add_u32_e32 v249, 0x14000, v151
	v_add_u32_e32 v250, 0x18000, v151
	v_add_u32_e32 v251, 0x1c000, v151
